# conversion engine v7 with plain (non-nt) transposed stores
# baseline (speedup 1.0000x reference)
; #define GAS __attribute__((address_space(1)))
; #define LAS __attribute__((address_space(3)))
; __device__ __forceinline__ void conv_store(const ConvItem& it, int lane, const f32x4 (&v)[4], LAS bf16* scr) {
;     ...
;     const int c = lane & 3;
; #pragma unroll
;     for (int j = 0; j < 2; ++j) { const int n = (lane >> 2) + 16 * j; const LAS bf16* sp = scr + (8 * c) * 34 + n;
;         v4u o; o.x = (unsigned)sp[0] | ((unsigned)sp[34] << 16); o.y = (unsigned)sp[68] | ((unsigned)sp[102] << 16); o.z = (unsigned)sp[136] | ((unsigned)sp[170] << 16); o.w = (unsigned)sp[204] | ((unsigned)sp[238] << 16);
;         const int ng = it.n0 + n; const int row = it.rowmode == 0 ? ng : ((ng >> 7) * 256 + (it.rowmode == 2 ? 128 : 0) + (ng & 127));
;         __builtin_nontemporal_store(o, (GAS v4u*)(it.WT + (size_t)row * it.ldt + it.k0 + 8 * c)); }
.Leng_st3:
	v_and_b32_e32 v254, 3, v1
	v_lshlrev_b32_e32 v254, 4, v254
	v_lshrrev_b32_e32 v255, 2, v1
	v_lshl_add_u32 v254, v255, 13, v254
	v_add_u32_e32 v255, 0x20000, v254
	v_lshl_or_b32 v232, v233, 16, v232
	v_lshl_or_b32 v233, v235, 16, v234
	v_lshl_or_b32 v234, v237, 16, v236
	v_lshl_or_b32 v235, v239, 16, v238
	v_lshl_or_b32 v236, v241, 16, v240
	v_lshl_or_b32 v237, v243, 16, v242
	v_lshl_or_b32 v238, v247, 16, v246
	v_lshl_or_b32 v239, v249, 16, v248
	s_and_b32 s98, s100, -2
	s_mov_b32 s99, s101
	global_store_dwordx4 v254, v[232:235], s[98:99]
	global_store_dwordx4 v255, v[236:239], s[98:99]
	s_mov_b32 s97, 2
